# nosleepbar on v117: the grid-barrier spin loops' s_sleep 1 removed as well
# baseline (speedup 1.0000x reference)
.LBB0_144:
	global_load_dword v17, v18, s[8:9] sc1
	global_load_dword v2, v18, s[10:11] sc1
	global_load_dword v3, v18, s[24:25] sc1
	global_load_dword v4, v18, s[26:27] sc1
	global_load_dword v5, v18, s[28:29] sc1
	global_load_dword v6, v18, s[30:31] sc1
	global_load_dword v7, v18, s[34:35] sc1
	global_load_dword v8, v18, s[36:37] sc1
	global_load_dword v9, v18, s[38:39] sc1
	global_load_dword v10, v18, s[40:41] sc1
	global_load_dword v11, v18, s[42:43] sc1
	global_load_dword v12, v18, s[44:45] sc1
	global_load_dword v13, v18, s[46:47] sc1
	global_load_dword v14, v18, s[48:49] sc1
	global_load_dword v15, v18, s[50:51] sc1
	global_load_dword v16, v18, s[62:63] sc1
	s_mov_b64 s[64:65], -1
	s_mov_b64 s[66:67], -1
	s_waitcnt vmcnt(14)
	v_add_u32_e32 v19, v2, v17
	s_waitcnt vmcnt(13)
	v_add_u32_e32 v19, v19, v3
	s_waitcnt vmcnt(12)
	v_add_u32_e32 v19, v19, v4
	s_waitcnt vmcnt(11)
	v_add_u32_e32 v19, v19, v5
	s_waitcnt vmcnt(10)
	v_add_u32_e32 v19, v19, v6
	s_waitcnt vmcnt(9)
	v_add_u32_e32 v19, v19, v7
	s_waitcnt vmcnt(8)
	v_add_u32_e32 v19, v19, v8
	s_waitcnt vmcnt(7)
	v_add_u32_e32 v19, v19, v9
	s_waitcnt vmcnt(6)
	v_add_u32_e32 v19, v19, v10
	s_waitcnt vmcnt(5)
	v_add_u32_e32 v19, v19, v11
	s_waitcnt vmcnt(4)
	v_add_u32_e32 v19, v19, v12
	s_waitcnt vmcnt(3)
	v_add_u32_e32 v19, v19, v13
	s_waitcnt vmcnt(2)
	v_add_u32_e32 v19, v19, v14
	s_waitcnt vmcnt(1)
	v_add_u32_e32 v19, v19, v15
	s_waitcnt vmcnt(0)
	v_add_u32_e32 v19, v19, v16
	v_cmp_eq_u32_e32 vcc, s2, v19
	s_cbranch_vccnz .LBB0_143
	s_and_b32 s12, s3, 0xff
	s_cmp_eq_u32 s12, 0
	s_mov_b64 s[72:73], -1
	s_nop 0
	s_cbranch_scc1 .LBB0_148
	s_and_b64 vcc, exec, s[72:73]
	s_cbranch_vccz .LBB0_143

.LBB0_160:
	s_and_b32 s3, s2, 0xff
	s_mov_b64 s[34:35], -1
	s_cmp_lg_u32 s3, 0
	s_mov_b64 s[38:39], -1
	s_nop 0
	s_cbranch_scc0 .LBB0_163
	s_and_b64 vcc, exec, s[38:39]
	s_cbranch_vccz .LBB0_159

.LBB0_177:
	s_and_b32 s3, s2, 0xff
	s_cmp_lg_u32 s3, 0
	s_mov_b64 s[36:37], -1
	s_nop 0
	s_cbranch_scc0 .LBB0_180
	s_mov_b64 s[38:39], -1
	s_and_b64 vcc, exec, s[36:37]
	s_cbranch_vccz .LBB0_176

.LBB0_295:
	global_load_dword v17, v18, s[8:9] sc1
	global_load_dword v2, v18, s[10:11] sc1
	global_load_dword v3, v18, s[24:25] sc1
	global_load_dword v4, v18, s[26:27] sc1
	global_load_dword v5, v18, s[28:29] sc1
	global_load_dword v6, v18, s[30:31] sc1
	global_load_dword v7, v18, s[34:35] sc1
	global_load_dword v8, v18, s[38:39] sc1
	global_load_dword v9, v18, s[40:41] sc1
	global_load_dword v10, v18, s[42:43] sc1
	global_load_dword v11, v18, s[44:45] sc1
	global_load_dword v12, v18, s[46:47] sc1
	global_load_dword v13, v18, s[48:49] sc1
	global_load_dword v14, v18, s[50:51] sc1
	global_load_dword v15, v18, s[62:63] sc1
	global_load_dword v16, v18, s[64:65] sc1
	s_mov_b64 s[66:67], -1
	s_mov_b64 s[72:73], -1
	s_waitcnt vmcnt(14)
	v_add_u32_e32 v19, v2, v17
	s_waitcnt vmcnt(13)
	v_add_u32_e32 v19, v19, v3
	s_waitcnt vmcnt(12)
	v_add_u32_e32 v19, v19, v4
	s_waitcnt vmcnt(11)
	v_add_u32_e32 v19, v19, v5
	s_waitcnt vmcnt(10)
	v_add_u32_e32 v19, v19, v6
	s_waitcnt vmcnt(9)
	v_add_u32_e32 v19, v19, v7
	s_waitcnt vmcnt(8)
	v_add_u32_e32 v19, v19, v8
	s_waitcnt vmcnt(7)
	v_add_u32_e32 v19, v19, v9
	s_waitcnt vmcnt(6)
	v_add_u32_e32 v19, v19, v10
	s_waitcnt vmcnt(5)
	v_add_u32_e32 v19, v19, v11
	s_waitcnt vmcnt(4)
	v_add_u32_e32 v19, v19, v12
	s_waitcnt vmcnt(3)
	v_add_u32_e32 v19, v19, v13
	s_waitcnt vmcnt(2)
	v_add_u32_e32 v19, v19, v14
	s_waitcnt vmcnt(1)
	v_add_u32_e32 v19, v19, v15
	s_waitcnt vmcnt(0)
	v_add_u32_e32 v19, v19, v16
	v_cmp_eq_u32_e32 vcc, s2, v19
	s_cbranch_vccnz .LBB0_294
	s_and_b32 s12, s3, 0xff
	s_cmp_eq_u32 s12, 0
	s_mov_b64 s[74:75], -1
	s_nop 0
	s_cbranch_scc1 .LBB0_299
	s_and_b64 vcc, exec, s[74:75]
	s_cbranch_vccz .LBB0_294

.LBB0_311:
	s_and_b32 s3, s2, 0xff
	s_mov_b64 s[34:35], -1
	s_cmp_lg_u32 s3, 0
	s_mov_b64 s[40:41], -1
	s_nop 0
	s_cbranch_scc0 .LBB0_314
	s_and_b64 vcc, exec, s[40:41]
	s_cbranch_vccz .LBB0_310

.LBB0_328:
	s_and_b32 s3, s2, 0xff
	s_cmp_lg_u32 s3, 0
	s_mov_b64 s[38:39], -1
	s_nop 0
	s_cbranch_scc0 .LBB0_331
	s_mov_b64 s[40:41], -1
	s_and_b64 vcc, exec, s[38:39]
	s_cbranch_vccz .LBB0_327

.LBB0_877:
	global_load_dword v17, v18, s[10:11] sc1
	global_load_dword v2, v18, s[12:13] sc1
	global_load_dword v3, v18, s[24:25] sc1
	global_load_dword v4, v18, s[26:27] sc1
	global_load_dword v5, v18, s[28:29] sc1
	global_load_dword v6, v18, s[30:31] sc1
	global_load_dword v7, v18, s[34:35] sc1
	global_load_dword v8, v18, s[38:39] sc1
	global_load_dword v9, v18, s[40:41] sc1
	global_load_dword v10, v18, s[44:45] sc1
	global_load_dword v11, v18, s[46:47] sc1
	global_load_dword v12, v18, s[48:49] sc1
	global_load_dword v13, v18, s[50:51] sc1
	global_load_dword v14, v18, s[58:59] sc1
	global_load_dword v15, v18, s[62:63] sc1
	global_load_dword v16, v18, s[64:65] sc1
	s_mov_b64 s[66:67], -1
	s_mov_b64 s[72:73], -1
	s_waitcnt vmcnt(14)
	v_add_u32_e32 v19, v2, v17
	s_waitcnt vmcnt(13)
	v_add_u32_e32 v19, v19, v3
	s_waitcnt vmcnt(12)
	v_add_u32_e32 v19, v19, v4
	s_waitcnt vmcnt(11)
	v_add_u32_e32 v19, v19, v5
	s_waitcnt vmcnt(10)
	v_add_u32_e32 v19, v19, v6
	s_waitcnt vmcnt(9)
	v_add_u32_e32 v19, v19, v7
	s_waitcnt vmcnt(8)
	v_add_u32_e32 v19, v19, v8
	s_waitcnt vmcnt(7)
	v_add_u32_e32 v19, v19, v9
	s_waitcnt vmcnt(6)
	v_add_u32_e32 v19, v19, v10
	s_waitcnt vmcnt(5)
	v_add_u32_e32 v19, v19, v11
	s_waitcnt vmcnt(4)
	v_add_u32_e32 v19, v19, v12
	s_waitcnt vmcnt(3)
	v_add_u32_e32 v19, v19, v13
	s_waitcnt vmcnt(2)
	v_add_u32_e32 v19, v19, v14
	s_waitcnt vmcnt(1)
	v_add_u32_e32 v19, v19, v15
	s_waitcnt vmcnt(0)
	v_add_u32_e32 v19, v19, v16
	v_cmp_eq_u32_e32 vcc, s2, v19
	s_cbranch_vccnz .LBB0_876
	s_and_b32 s14, s3, 0xff
	s_cmp_eq_u32 s14, 0
	s_mov_b64 s[74:75], -1
	s_nop 0
	s_cbranch_scc1 .LBB0_881
	s_and_b64 vcc, exec, s[74:75]
	s_cbranch_vccz .LBB0_876

.LBB0_1240:
	global_load_dword v17, v18, s[10:11] sc1
	global_load_dword v2, v18, s[12:13] sc1
	global_load_dword v3, v18, s[14:15] sc1
	global_load_dword v4, v18, s[16:17] sc1
	global_load_dword v5, v18, s[24:25] sc1
	global_load_dword v6, v18, s[26:27] sc1
	global_load_dword v7, v18, s[28:29] sc1
	global_load_dword v8, v18, s[30:31] sc1
	global_load_dword v9, v18, s[34:35] sc1
	global_load_dword v10, v18, s[38:39] sc1
	global_load_dword v11, v18, s[40:41] sc1
	global_load_dword v12, v18, s[44:45] sc1
	global_load_dword v13, v18, s[46:47] sc1
	global_load_dword v14, v18, s[48:49] sc1
	global_load_dword v15, v18, s[50:51] sc1
	global_load_dword v16, v18, s[54:55] sc1
	s_mov_b64 s[56:57], -1
	s_mov_b64 s[58:59], -1
	s_waitcnt vmcnt(14)
	v_add_u32_e32 v19, v2, v17
	s_waitcnt vmcnt(13)
	v_add_u32_e32 v19, v19, v3
	s_waitcnt vmcnt(12)
	v_add_u32_e32 v19, v19, v4
	s_waitcnt vmcnt(11)
	v_add_u32_e32 v19, v19, v5
	s_waitcnt vmcnt(10)
	v_add_u32_e32 v19, v19, v6
	s_waitcnt vmcnt(9)
	v_add_u32_e32 v19, v19, v7
	s_waitcnt vmcnt(8)
	v_add_u32_e32 v19, v19, v8
	s_waitcnt vmcnt(7)
	v_add_u32_e32 v19, v19, v9
	s_waitcnt vmcnt(6)
	v_add_u32_e32 v19, v19, v10
	s_waitcnt vmcnt(5)
	v_add_u32_e32 v19, v19, v11
	s_waitcnt vmcnt(4)
	v_add_u32_e32 v19, v19, v12
	s_waitcnt vmcnt(3)
	v_add_u32_e32 v19, v19, v13
	s_waitcnt vmcnt(2)
	v_add_u32_e32 v19, v19, v14
	s_waitcnt vmcnt(1)
	v_add_u32_e32 v19, v19, v15
	s_waitcnt vmcnt(0)
	v_add_u32_e32 v19, v19, v16
	v_cmp_eq_u32_e32 vcc, s2, v19
	s_cbranch_vccnz .LBB0_1239
	s_and_b32 s18, s3, 0xff
	s_cmp_eq_u32 s18, 0
	s_mov_b64 s[60:61], -1
	s_nop 0
	s_cbranch_scc1 .LBB0_1244
	s_and_b64 vcc, exec, s[60:61]
	s_cbranch_vccz .LBB0_1239

.LBB0_1256:
	s_and_b32 s3, s2, 0xff
	s_mov_b64 s[28:29], -1
	s_cmp_lg_u32 s3, 0
	s_mov_b64 s[34:35], -1
	s_nop 0
	s_cbranch_scc0 .LBB0_1259
	s_and_b64 vcc, exec, s[34:35]
	s_cbranch_vccz .LBB0_1255

.LBB0_1273:
	s_and_b32 s3, s2, 0xff
	s_cmp_lg_u32 s3, 0
	s_mov_b64 s[30:31], -1
	s_nop 0
	s_cbranch_scc0 .LBB0_1276
	s_mov_b64 s[34:35], -1
	s_and_b64 vcc, exec, s[30:31]
	s_cbranch_vccz .LBB0_1272

.LBB0_1365:
	global_load_dword v17, v18, s[8:9] sc1
	global_load_dword v2, v18, s[10:11] sc1
	global_load_dword v3, v18, s[12:13] sc1
	global_load_dword v4, v18, s[14:15] sc1
	global_load_dword v5, v18, s[16:17] sc1
	global_load_dword v6, v18, s[24:25] sc1
	global_load_dword v7, v18, s[26:27] sc1
	global_load_dword v8, v18, s[28:29] sc1
	global_load_dword v9, v18, s[30:31] sc1
	global_load_dword v10, v18, s[34:35] sc1
	global_load_dword v11, v18, s[38:39] sc1
	global_load_dword v12, v18, s[40:41] sc1
	global_load_dword v13, v18, s[44:45] sc1
	global_load_dword v14, v18, s[46:47] sc1
	global_load_dword v15, v18, s[48:49] sc1
	global_load_dword v16, v18, s[50:51] sc1
	s_mov_b64 s[54:55], -1
	s_mov_b64 s[56:57], -1
	s_waitcnt vmcnt(14)
	v_add_u32_e32 v19, v2, v17
	s_waitcnt vmcnt(13)
	v_add_u32_e32 v19, v19, v3
	s_waitcnt vmcnt(12)
	v_add_u32_e32 v19, v19, v4
	s_waitcnt vmcnt(11)
	v_add_u32_e32 v19, v19, v5
	s_waitcnt vmcnt(10)
	v_add_u32_e32 v19, v19, v6
	s_waitcnt vmcnt(9)
	v_add_u32_e32 v19, v19, v7
	s_waitcnt vmcnt(8)
	v_add_u32_e32 v19, v19, v8
	s_waitcnt vmcnt(7)
	v_add_u32_e32 v19, v19, v9
	s_waitcnt vmcnt(6)
	v_add_u32_e32 v19, v19, v10
	s_waitcnt vmcnt(5)
	v_add_u32_e32 v19, v19, v11
	s_waitcnt vmcnt(4)
	v_add_u32_e32 v19, v19, v12
	s_waitcnt vmcnt(3)
	v_add_u32_e32 v19, v19, v13
	s_waitcnt vmcnt(2)
	v_add_u32_e32 v19, v19, v14
	s_waitcnt vmcnt(1)
	v_add_u32_e32 v19, v19, v15
	s_waitcnt vmcnt(0)
	v_add_u32_e32 v19, v19, v16
	v_cmp_eq_u32_e32 vcc, s2, v19
	s_cbranch_vccnz .LBB0_1364
	s_and_b32 s18, s3, 0xff
	s_cmp_eq_u32 s18, 0
	s_mov_b64 s[58:59], -1
	s_nop 0
	s_cbranch_scc1 .LBB0_1369
	s_and_b64 vcc, exec, s[58:59]
	s_cbranch_vccz .LBB0_1364

.LBB0_1381:
	s_and_b32 s3, s2, 0xff
	s_mov_b64 s[26:27], -1
	s_cmp_lg_u32 s3, 0
	s_mov_b64 s[30:31], -1
	s_nop 0
	s_cbranch_scc0 .LBB0_1384
	s_and_b64 vcc, exec, s[30:31]
	s_cbranch_vccz .LBB0_1380

.LBB0_1398:
	s_and_b32 s3, s2, 0xff
	s_cmp_lg_u32 s3, 0
	s_mov_b64 s[28:29], -1
	s_nop 0
	s_cbranch_scc0 .LBB0_1401
	s_mov_b64 s[30:31], -1
	s_and_b64 vcc, exec, s[28:29]
	s_cbranch_vccz .LBB0_1397

.LBB0_2042:
	global_load_dword v17, v18, s[8:9] sc1
	global_load_dword v2, v18, s[10:11] sc1
	global_load_dword v3, v18, s[12:13] sc1
	global_load_dword v4, v18, s[14:15] sc1
	global_load_dword v5, v18, s[16:17] sc1
	global_load_dword v6, v18, s[18:19] sc1
	global_load_dword v7, v18, s[20:21] sc1
	global_load_dword v8, v18, s[22:23] sc1
	global_load_dword v9, v18, s[24:25] sc1
	global_load_dword v10, v18, s[26:27] sc1
	global_load_dword v11, v18, s[28:29] sc1
	global_load_dword v12, v18, s[30:31] sc1
	global_load_dword v13, v18, s[34:35] sc1
	global_load_dword v14, v18, s[38:39] sc1
	global_load_dword v15, v18, s[40:41] sc1
	global_load_dword v16, v18, s[44:45] sc1
	s_mov_b64 s[46:47], -1
	s_mov_b64 s[48:49], -1
	s_waitcnt vmcnt(14)
	v_add_u32_e32 v19, v2, v17
	s_waitcnt vmcnt(13)
	v_add_u32_e32 v19, v19, v3
	s_waitcnt vmcnt(12)
	v_add_u32_e32 v19, v19, v4
	s_waitcnt vmcnt(11)
	v_add_u32_e32 v19, v19, v5
	s_waitcnt vmcnt(10)
	v_add_u32_e32 v19, v19, v6
	s_waitcnt vmcnt(9)
	v_add_u32_e32 v19, v19, v7
	s_waitcnt vmcnt(8)
	v_add_u32_e32 v19, v19, v8
	s_waitcnt vmcnt(7)
	v_add_u32_e32 v19, v19, v9
	s_waitcnt vmcnt(6)
	v_add_u32_e32 v19, v19, v10
	s_waitcnt vmcnt(5)
	v_add_u32_e32 v19, v19, v11
	s_waitcnt vmcnt(4)
	v_add_u32_e32 v19, v19, v12
	s_waitcnt vmcnt(3)
	v_add_u32_e32 v19, v19, v13
	s_waitcnt vmcnt(2)
	v_add_u32_e32 v19, v19, v14
	s_waitcnt vmcnt(1)
	v_add_u32_e32 v19, v19, v15
	s_waitcnt vmcnt(0)
	v_add_u32_e32 v19, v19, v16
	v_cmp_eq_u32_e32 vcc, s2, v19
	s_cbranch_vccnz .LBB0_2041
	s_and_b32 s33, s3, 0xff
	s_cmp_eq_u32 s33, 0
	s_mov_b64 s[50:51], -1
	s_nop 0
	s_cbranch_scc1 .LBB0_2046
	s_and_b64 vcc, exec, s[50:51]
	s_cbranch_vccz .LBB0_2041

.LBB0_2058:
	s_and_b32 s3, s2, 0xff
	s_mov_b64 s[20:21], -1
	s_cmp_lg_u32 s3, 0
	s_mov_b64 s[24:25], -1
	s_nop 0
	s_cbranch_scc0 .LBB0_2061
	s_and_b64 vcc, exec, s[24:25]
	s_cbranch_vccz .LBB0_2057

.LBB0_2075:
	s_and_b32 s3, s2, 0xff
	s_cmp_lg_u32 s3, 0
	s_mov_b64 s[22:23], -1
	s_nop 0
	s_cbranch_scc0 .LBB0_2078
	s_mov_b64 s[24:25], -1
	s_and_b64 vcc, exec, s[22:23]
	s_cbranch_vccz .LBB0_2074

.LBB0_2206:
	global_load_dword v15, v16, s[4:5] sc1
	global_load_dword v0, v16, s[6:7] sc1
	global_load_dword v1, v16, s[8:9] sc1
	global_load_dword v2, v16, s[10:11] sc1
	global_load_dword v3, v16, s[12:13] sc1
	global_load_dword v4, v16, s[14:15] sc1
	global_load_dword v5, v16, s[16:17] sc1
	global_load_dword v6, v16, s[18:19] sc1
	global_load_dword v7, v16, s[20:21] sc1
	global_load_dword v8, v16, s[22:23] sc1
	global_load_dword v9, v16, s[24:25] sc1
	global_load_dword v10, v16, s[26:27] sc1
	global_load_dword v11, v16, s[28:29] sc1
	global_load_dword v12, v16, s[30:31] sc1
	global_load_dword v13, v16, s[34:35] sc1
	global_load_dword v14, v16, s[36:37] sc1
	s_mov_b64 s[38:39], -1
	s_mov_b64 s[40:41], -1
	s_waitcnt vmcnt(14)
	v_add_u32_e32 v17, v0, v15
	s_waitcnt vmcnt(13)
	v_add_u32_e32 v17, v17, v1
	s_waitcnt vmcnt(12)
	v_add_u32_e32 v17, v17, v2
	s_waitcnt vmcnt(11)
	v_add_u32_e32 v17, v17, v3
	s_waitcnt vmcnt(10)
	v_add_u32_e32 v17, v17, v4
	s_waitcnt vmcnt(9)
	v_add_u32_e32 v17, v17, v5
	s_waitcnt vmcnt(8)
	v_add_u32_e32 v17, v17, v6
	s_waitcnt vmcnt(7)
	v_add_u32_e32 v17, v17, v7
	s_waitcnt vmcnt(6)
	v_add_u32_e32 v17, v17, v8
	s_waitcnt vmcnt(5)
	v_add_u32_e32 v17, v17, v9
	s_waitcnt vmcnt(4)
	v_add_u32_e32 v17, v17, v10
	s_waitcnt vmcnt(3)
	v_add_u32_e32 v17, v17, v11
	s_waitcnt vmcnt(2)
	v_add_u32_e32 v17, v17, v12
	s_waitcnt vmcnt(1)
	v_add_u32_e32 v17, v17, v13
	s_waitcnt vmcnt(0)
	v_add_u32_e32 v17, v17, v14
	v_cmp_eq_u32_e32 vcc, s33, v17
	s_cbranch_vccnz .LBB0_2205
	s_and_b32 s38, s44, 0xff
	s_cmp_eq_u32 s38, 0
	s_mov_b64 s[38:39], -1
	s_mov_b64 s[42:43], -1
	s_nop 0
	s_cbranch_scc1 .LBB0_2210
	s_and_b64 vcc, exec, s[42:43]
	s_cbranch_vccz .LBB0_2205

.LBB0_2222:
	s_and_b32 s18, s22, 0xff
	s_mov_b64 s[16:17], -1
	s_cmp_lg_u32 s18, 0
	s_mov_b64 s[20:21], -1
	s_nop 0
	s_cbranch_scc0 .LBB0_2225
	s_and_b64 vcc, exec, s[20:21]
	s_cbranch_vccz .LBB0_2221

.LBB0_2239:
	s_and_b32 s16, s22, 0xff
	s_cmp_lg_u32 s16, 0
	s_mov_b64 s[18:19], -1
	s_nop 0
	s_cbranch_scc0 .LBB0_2242
	s_mov_b64 s[20:21], -1
	s_and_b64 vcc, exec, s[18:19]
	s_cbranch_vccz .LBB0_2238
